# kind-0 (sigmoid gates) epilogue hand-written straight-line: same arithmetic, immediate-offset addressing, no per-tile scalar branching
# baseline (speedup 1.0000x reference)
; __device__ __forceinline__ u32x2 pack4(f32x4 v) { u32x2 r; r[0] = cvt_pk(v[0], v[1]); r[1] = cvt_pk(v[2], v[3]); return r; }
; __device__ __forceinline__ float sigmoidf_(float x) { return __builtin_amdgcn_rcpf(1.0f + __expf(-x)); }
; __device__ __forceinline__ float gelu_tanh(float x) { const float z = 1.5957691216057308f * (x + 0.044715f * x * x * x); return x * sigmoidf_(z); }
; __device__ __forceinline__ float siluf_(float x) { return x * sigmoidf_(x); }
; __device__ __forceinline__ void epilogue(const Params& p, const Unit& u, const f32x4 (&acc)[2][2][4][2], int wr, int wc, int fr, int fq) {
;     ...
; #pragma unroll
;     for (int ai = 0; ai < 2; ++ai)
; #pragma unroll
;       for (int m = 0; m < 4; ++m) {
;         bf16_t* rp = dst + (size_t)(row0 + ai * 128 + m * 16) * ld + cb + ct0;
; #pragma unroll
;         for (int bj = 0; bj < 2; ++bj)
; #pragma unroll
;           for (int n = 0; n < 2; ++n) {
;             f32x4 v = acc[ai][bj][m][n];
;             if (act == 1) { v[0] = sigmoidf_(v[0]); v[1] = sigmoidf_(v[1]); v[2] = sigmoidf_(v[2]); v[3] = sigmoidf_(v[3]); }
;             else if (act == 2) { v[0] = gelu_tanh(v[0]); v[1] = gelu_tanh(v[1]); v[2] = gelu_tanh(v[2]); v[3] = gelu_tanh(v[3]); }
;             else if (act == 3) { v[0] = siluf_(v[0]); v[1] = siluf_(v[1]); v[2] = siluf_(v[2]); v[3] = siluf_(v[3]); }
;             else { v = v * scale; }
;             *(u32x2*)(rp + bj * 128 + n * 16) = pack4(v);
;           }
.Lk0_ep:
	s_add_u32 s34, s24, 0xc709000
	s_addc_u32 s35, s25, 0
	v_lshl_or_b32 v64, s78, 8, v174
	v_mul_u32_u24_e32 v67, 0x3000, v66
	v_lshl_add_u32 v64, v64, 1, v67
	s_mov_b32 s30, 0xbfb8aa3b
	v_mul_f32_e32 v128, s30, v128
	v_mul_f32_e32 v129, s30, v129
	v_mul_f32_e32 v130, s30, v130
	v_mul_f32_e32 v131, s30, v131
	v_exp_f32_e32 v128, v128
	v_exp_f32_e32 v129, v129
	v_exp_f32_e32 v130, v130
	v_exp_f32_e32 v131, v131
	v_add_f32_e32 v128, 1.0, v128
	v_add_f32_e32 v129, 1.0, v129
	v_add_f32_e32 v130, 1.0, v130
	v_add_f32_e32 v131, 1.0, v131
	v_rcp_f32_e32 v128, v128
	v_rcp_f32_e32 v129, v129
	v_rcp_f32_e32 v130, v130
	v_rcp_f32_e32 v131, v131
	v_cvt_pk_bf16_f32 v132, v128, v129
	v_cvt_pk_bf16_f32 v133, v130, v131
	global_store_dwordx2 v64, v[132:133], s[34:35] offset:0
	v_mul_f32_e32 v124, s30, v124
	v_mul_f32_e32 v125, s30, v125
	v_mul_f32_e32 v126, s30, v126
	v_mul_f32_e32 v127, s30, v127
	v_exp_f32_e32 v124, v124
	v_exp_f32_e32 v125, v125
	v_exp_f32_e32 v126, v126
	v_exp_f32_e32 v127, v127
	v_add_f32_e32 v124, 1.0, v124
	v_add_f32_e32 v125, 1.0, v125
	v_add_f32_e32 v126, 1.0, v126
	v_add_f32_e32 v127, 1.0, v127
	v_rcp_f32_e32 v124, v124
	v_rcp_f32_e32 v125, v125
	v_rcp_f32_e32 v126, v126
	v_rcp_f32_e32 v127, v127
	v_cvt_pk_bf16_f32 v134, v124, v125
	v_cvt_pk_bf16_f32 v135, v126, v127
	global_store_dwordx2 v64, v[134:135], s[34:35] offset:32
	v_mul_f32_e32 v96, s30, v96
	v_mul_f32_e32 v97, s30, v97
	v_mul_f32_e32 v98, s30, v98
	v_mul_f32_e32 v99, s30, v99
	v_exp_f32_e32 v96, v96
	v_exp_f32_e32 v97, v97
	v_exp_f32_e32 v98, v98
	v_exp_f32_e32 v99, v99
	v_add_f32_e32 v96, 1.0, v96
	v_add_f32_e32 v97, 1.0, v97
	v_add_f32_e32 v98, 1.0, v98
	v_add_f32_e32 v99, 1.0, v99
	v_rcp_f32_e32 v96, v96
	v_rcp_f32_e32 v97, v97
	v_rcp_f32_e32 v98, v98
	v_rcp_f32_e32 v99, v99
	v_cvt_pk_bf16_f32 v136, v96, v97
	v_cvt_pk_bf16_f32 v137, v98, v99
	global_store_dwordx2 v64, v[136:137], s[34:35] offset:256
	v_mul_f32_e32 v92, s30, v92
	v_mul_f32_e32 v93, s30, v93
	v_mul_f32_e32 v94, s30, v94
	v_mul_f32_e32 v95, s30, v95
	v_exp_f32_e32 v92, v92
	v_exp_f32_e32 v93, v93
	v_exp_f32_e32 v94, v94
	v_exp_f32_e32 v95, v95
	v_add_f32_e32 v92, 1.0, v92
	v_add_f32_e32 v93, 1.0, v93
	v_add_f32_e32 v94, 1.0, v94
	v_add_f32_e32 v95, 1.0, v95
	v_rcp_f32_e32 v92, v92
	v_rcp_f32_e32 v93, v93
	v_rcp_f32_e32 v94, v94
	v_rcp_f32_e32 v95, v95
	v_cvt_pk_bf16_f32 v138, v92, v93
	v_cvt_pk_bf16_f32 v139, v94, v95
	global_store_dwordx2 v64, v[138:139], s[34:35] offset:288
	v_add_u32_e32 v64, 0x30000, v64
	v_mul_f32_e32 v120, s30, v120
	v_mul_f32_e32 v121, s30, v121
	v_mul_f32_e32 v122, s30, v122
	v_mul_f32_e32 v123, s30, v123
	v_exp_f32_e32 v120, v120
	v_exp_f32_e32 v121, v121
	v_exp_f32_e32 v122, v122
	v_exp_f32_e32 v123, v123
	v_add_f32_e32 v120, 1.0, v120
	v_add_f32_e32 v121, 1.0, v121
	v_add_f32_e32 v122, 1.0, v122
	v_add_f32_e32 v123, 1.0, v123
	v_rcp_f32_e32 v120, v120
	v_rcp_f32_e32 v121, v121
	v_rcp_f32_e32 v122, v122
	v_rcp_f32_e32 v123, v123
	v_cvt_pk_bf16_f32 v140, v120, v121
	v_cvt_pk_bf16_f32 v141, v122, v123
	global_store_dwordx2 v64, v[140:141], s[34:35] offset:0
	v_mul_f32_e32 v116, s30, v116
	v_mul_f32_e32 v117, s30, v117
	v_mul_f32_e32 v118, s30, v118
	v_mul_f32_e32 v119, s30, v119
	v_exp_f32_e32 v116, v116
	v_exp_f32_e32 v117, v117
	v_exp_f32_e32 v118, v118
	v_exp_f32_e32 v119, v119
	v_add_f32_e32 v116, 1.0, v116
	v_add_f32_e32 v117, 1.0, v117
	v_add_f32_e32 v118, 1.0, v118
	v_add_f32_e32 v119, 1.0, v119
	v_rcp_f32_e32 v116, v116
	v_rcp_f32_e32 v117, v117
	v_rcp_f32_e32 v118, v118
	v_rcp_f32_e32 v119, v119
	v_cvt_pk_bf16_f32 v142, v116, v117
	v_cvt_pk_bf16_f32 v143, v118, v119
	global_store_dwordx2 v64, v[142:143], s[34:35] offset:32
	v_mul_f32_e32 v88, s30, v88
	v_mul_f32_e32 v89, s30, v89
	v_mul_f32_e32 v90, s30, v90
	v_mul_f32_e32 v91, s30, v91
	v_exp_f32_e32 v88, v88
	v_exp_f32_e32 v89, v89
	v_exp_f32_e32 v90, v90
	v_exp_f32_e32 v91, v91
	v_add_f32_e32 v88, 1.0, v88
	v_add_f32_e32 v89, 1.0, v89
	v_add_f32_e32 v90, 1.0, v90
	v_add_f32_e32 v91, 1.0, v91
	v_rcp_f32_e32 v88, v88
	v_rcp_f32_e32 v89, v89
	v_rcp_f32_e32 v90, v90
	v_rcp_f32_e32 v91, v91
	v_cvt_pk_bf16_f32 v144, v88, v89
	v_cvt_pk_bf16_f32 v145, v90, v91
	global_store_dwordx2 v64, v[144:145], s[34:35] offset:256
	v_mul_f32_e32 v84, s30, v84
	v_mul_f32_e32 v85, s30, v85
	v_mul_f32_e32 v86, s30, v86
	v_mul_f32_e32 v87, s30, v87
	v_exp_f32_e32 v84, v84
	v_exp_f32_e32 v85, v85
	v_exp_f32_e32 v86, v86
	v_exp_f32_e32 v87, v87
	v_add_f32_e32 v84, 1.0, v84
	v_add_f32_e32 v85, 1.0, v85
	v_add_f32_e32 v86, 1.0, v86
	v_add_f32_e32 v87, 1.0, v87
	v_rcp_f32_e32 v84, v84
	v_rcp_f32_e32 v85, v85
	v_rcp_f32_e32 v86, v86
	v_rcp_f32_e32 v87, v87
	v_cvt_pk_bf16_f32 v146, v84, v85
	v_cvt_pk_bf16_f32 v147, v86, v87
	global_store_dwordx2 v64, v[146:147], s[34:35] offset:288
	v_add_u32_e32 v64, 0x30000, v64
	v_mul_f32_e32 v112, s30, v112
	v_mul_f32_e32 v113, s30, v113
	v_mul_f32_e32 v114, s30, v114
	v_mul_f32_e32 v115, s30, v115
	v_exp_f32_e32 v112, v112
	v_exp_f32_e32 v113, v113
	v_exp_f32_e32 v114, v114
	v_exp_f32_e32 v115, v115
	v_add_f32_e32 v112, 1.0, v112
	v_add_f32_e32 v113, 1.0, v113
	v_add_f32_e32 v114, 1.0, v114
	v_add_f32_e32 v115, 1.0, v115
	v_rcp_f32_e32 v112, v112
	v_rcp_f32_e32 v113, v113
	v_rcp_f32_e32 v114, v114
	v_rcp_f32_e32 v115, v115
	v_cvt_pk_bf16_f32 v132, v112, v113
	v_cvt_pk_bf16_f32 v133, v114, v115
	global_store_dwordx2 v64, v[132:133], s[34:35] offset:0
	v_mul_f32_e32 v108, s30, v108
	v_mul_f32_e32 v109, s30, v109
	v_mul_f32_e32 v110, s30, v110
	v_mul_f32_e32 v111, s30, v111
	v_exp_f32_e32 v108, v108
	v_exp_f32_e32 v109, v109
	v_exp_f32_e32 v110, v110
	v_exp_f32_e32 v111, v111
	v_add_f32_e32 v108, 1.0, v108
; __device__ __forceinline__ u32x2 pack4(f32x4 v) { u32x2 r; r[0] = cvt_pk(v[0], v[1]); r[1] = cvt_pk(v[2], v[3]); return r; }
; __device__ __forceinline__ float sigmoidf_(float x) { return __builtin_amdgcn_rcpf(1.0f + __expf(-x)); }
; __device__ __forceinline__ float gelu_tanh(float x) { const float z = 1.5957691216057308f * (x + 0.044715f * x * x * x); return x * sigmoidf_(z); }
; __device__ __forceinline__ float siluf_(float x) { return x * sigmoidf_(x); }
; __device__ __forceinline__ void epilogue(const Params& p, const Unit& u, const f32x4 (&acc)[2][2][4][2], int wr, int wc, int fr, int fq) {
;     ...
; #pragma unroll
;     for (int ai = 0; ai < 2; ++ai)
; #pragma unroll
;       for (int m = 0; m < 4; ++m) {
;         bf16_t* rp = dst + (size_t)(row0 + ai * 128 + m * 16) * ld + cb + ct0;
; #pragma unroll
;         for (int bj = 0; bj < 2; ++bj)
; #pragma unroll
;           for (int n = 0; n < 2; ++n) {
;             f32x4 v = acc[ai][bj][m][n];
;             if (act == 1) { v[0] = sigmoidf_(v[0]); v[1] = sigmoidf_(v[1]); v[2] = sigmoidf_(v[2]); v[3] = sigmoidf_(v[3]); }
;             else if (act == 2) { v[0] = gelu_tanh(v[0]); v[1] = gelu_tanh(v[1]); v[2] = gelu_tanh(v[2]); v[3] = gelu_tanh(v[3]); }
;             else if (act == 3) { v[0] = siluf_(v[0]); v[1] = siluf_(v[1]); v[2] = siluf_(v[2]); v[3] = siluf_(v[3]); }
;             else { v = v * scale; }
;             *(u32x2*)(rp + bj * 128 + n * 16) = pack4(v);
;           }
	v_add_f32_e32 v109, 1.0, v109
	v_add_f32_e32 v110, 1.0, v110
	v_add_f32_e32 v111, 1.0, v111
	v_rcp_f32_e32 v108, v108
	v_rcp_f32_e32 v109, v109
	v_rcp_f32_e32 v110, v110
	v_rcp_f32_e32 v111, v111
	v_cvt_pk_bf16_f32 v134, v108, v109
	v_cvt_pk_bf16_f32 v135, v110, v111
	global_store_dwordx2 v64, v[134:135], s[34:35] offset:32
	v_mul_f32_e32 v80, s30, v80
	v_mul_f32_e32 v81, s30, v81
	v_mul_f32_e32 v82, s30, v82
	v_mul_f32_e32 v83, s30, v83
	v_exp_f32_e32 v80, v80
	v_exp_f32_e32 v81, v81
	v_exp_f32_e32 v82, v82
	v_exp_f32_e32 v83, v83
	v_add_f32_e32 v80, 1.0, v80
	v_add_f32_e32 v81, 1.0, v81
	v_add_f32_e32 v82, 1.0, v82
	v_add_f32_e32 v83, 1.0, v83
	v_rcp_f32_e32 v80, v80
	v_rcp_f32_e32 v81, v81
	v_rcp_f32_e32 v82, v82
	v_rcp_f32_e32 v83, v83
	v_cvt_pk_bf16_f32 v136, v80, v81
	v_cvt_pk_bf16_f32 v137, v82, v83
	global_store_dwordx2 v64, v[136:137], s[34:35] offset:256
	v_mul_f32_e32 v76, s30, v76
	v_mul_f32_e32 v77, s30, v77
	v_mul_f32_e32 v78, s30, v78
	v_mul_f32_e32 v79, s30, v79
	v_exp_f32_e32 v76, v76
	v_exp_f32_e32 v77, v77
	v_exp_f32_e32 v78, v78
	v_exp_f32_e32 v79, v79
	v_add_f32_e32 v76, 1.0, v76
	v_add_f32_e32 v77, 1.0, v77
	v_add_f32_e32 v78, 1.0, v78
	v_add_f32_e32 v79, 1.0, v79
	v_rcp_f32_e32 v76, v76
	v_rcp_f32_e32 v77, v77
	v_rcp_f32_e32 v78, v78
	v_rcp_f32_e32 v79, v79
	v_cvt_pk_bf16_f32 v138, v76, v77
	v_cvt_pk_bf16_f32 v139, v78, v79
	global_store_dwordx2 v64, v[138:139], s[34:35] offset:288
	v_add_u32_e32 v64, 0x30000, v64
	v_mul_f32_e32 v104, s30, v104
	v_mul_f32_e32 v105, s30, v105
	v_mul_f32_e32 v106, s30, v106
	v_mul_f32_e32 v107, s30, v107
	v_exp_f32_e32 v104, v104
	v_exp_f32_e32 v105, v105
	v_exp_f32_e32 v106, v106
	v_exp_f32_e32 v107, v107
	v_add_f32_e32 v104, 1.0, v104
	v_add_f32_e32 v105, 1.0, v105
	v_add_f32_e32 v106, 1.0, v106
	v_add_f32_e32 v107, 1.0, v107
	v_rcp_f32_e32 v104, v104
	v_rcp_f32_e32 v105, v105
	v_rcp_f32_e32 v106, v106
	v_rcp_f32_e32 v107, v107
	v_cvt_pk_bf16_f32 v140, v104, v105
	v_cvt_pk_bf16_f32 v141, v106, v107
	global_store_dwordx2 v64, v[140:141], s[34:35] offset:0
	v_mul_f32_e32 v100, s30, v100
	v_mul_f32_e32 v101, s30, v101
	v_mul_f32_e32 v102, s30, v102
	v_mul_f32_e32 v103, s30, v103
	v_exp_f32_e32 v100, v100
	v_exp_f32_e32 v101, v101
	v_exp_f32_e32 v102, v102
	v_exp_f32_e32 v103, v103
	v_add_f32_e32 v100, 1.0, v100
	v_add_f32_e32 v101, 1.0, v101
	v_add_f32_e32 v102, 1.0, v102
	v_add_f32_e32 v103, 1.0, v103
	v_rcp_f32_e32 v100, v100
	v_rcp_f32_e32 v101, v101
	v_rcp_f32_e32 v102, v102
	v_rcp_f32_e32 v103, v103
	v_cvt_pk_bf16_f32 v142, v100, v101
	v_cvt_pk_bf16_f32 v143, v102, v103
	global_store_dwordx2 v64, v[142:143], s[34:35] offset:32
	v_mul_f32_e32 v72, s30, v72
	v_mul_f32_e32 v73, s30, v73
	v_mul_f32_e32 v74, s30, v74
	v_mul_f32_e32 v75, s30, v75
	v_exp_f32_e32 v72, v72
	v_exp_f32_e32 v73, v73
	v_exp_f32_e32 v74, v74
	v_exp_f32_e32 v75, v75
	v_add_f32_e32 v72, 1.0, v72
	v_add_f32_e32 v73, 1.0, v73
	v_add_f32_e32 v74, 1.0, v74
	v_add_f32_e32 v75, 1.0, v75
	v_rcp_f32_e32 v72, v72
	v_rcp_f32_e32 v73, v73
	v_rcp_f32_e32 v74, v74
	v_rcp_f32_e32 v75, v75
	v_cvt_pk_bf16_f32 v144, v72, v73
	v_cvt_pk_bf16_f32 v145, v74, v75
	global_store_dwordx2 v64, v[144:145], s[34:35] offset:256
	v_mul_f32_e32 v68, s30, v68
	v_mul_f32_e32 v69, s30, v69
	v_mul_f32_e32 v70, s30, v70
	v_mul_f32_e32 v71, s30, v71
	v_exp_f32_e32 v68, v68
	v_exp_f32_e32 v69, v69
	v_exp_f32_e32 v70, v70
	v_exp_f32_e32 v71, v71
	v_add_f32_e32 v68, 1.0, v68
	v_add_f32_e32 v69, 1.0, v69
	v_add_f32_e32 v70, 1.0, v70
	v_add_f32_e32 v71, 1.0, v71
	v_rcp_f32_e32 v68, v68
	v_rcp_f32_e32 v69, v69
	v_rcp_f32_e32 v70, v70
	v_rcp_f32_e32 v71, v71
	v_cvt_pk_bf16_f32 v146, v68, v69
	v_cvt_pk_bf16_f32 v147, v70, v71
	global_store_dwordx2 v64, v[146:147], s[34:35] offset:288
	v_add_u32_e32 v64, 0xf0000, v64
	v_mul_f32_e32 v60, s30, v60
	v_mul_f32_e32 v61, s30, v61
	v_mul_f32_e32 v62, s30, v62
	v_mul_f32_e32 v63, s30, v63
	v_exp_f32_e32 v60, v60
	v_exp_f32_e32 v61, v61
	v_exp_f32_e32 v62, v62
	v_exp_f32_e32 v63, v63
	v_add_f32_e32 v60, 1.0, v60
	v_add_f32_e32 v61, 1.0, v61
	v_add_f32_e32 v62, 1.0, v62
	v_add_f32_e32 v63, 1.0, v63
	v_rcp_f32_e32 v60, v60
	v_rcp_f32_e32 v61, v61
	v_rcp_f32_e32 v62, v62
	v_rcp_f32_e32 v63, v63
	v_cvt_pk_bf16_f32 v132, v60, v61
	v_cvt_pk_bf16_f32 v133, v62, v63
	global_store_dwordx2 v64, v[132:133], s[34:35] offset:0
	v_mul_f32_e32 v56, s30, v56
	v_mul_f32_e32 v57, s30, v57
	v_mul_f32_e32 v58, s30, v58
	v_mul_f32_e32 v59, s30, v59
	v_exp_f32_e32 v56, v56
	v_exp_f32_e32 v57, v57
	v_exp_f32_e32 v58, v58
	v_exp_f32_e32 v59, v59
	v_add_f32_e32 v56, 1.0, v56
	v_add_f32_e32 v57, 1.0, v57
	v_add_f32_e32 v58, 1.0, v58
	v_add_f32_e32 v59, 1.0, v59
	v_rcp_f32_e32 v56, v56
	v_rcp_f32_e32 v57, v57
	v_rcp_f32_e32 v58, v58
	v_rcp_f32_e32 v59, v59
	v_cvt_pk_bf16_f32 v134, v56, v57
	v_cvt_pk_bf16_f32 v135, v58, v59
	global_store_dwordx2 v64, v[134:135], s[34:35] offset:32
	v_mul_f32_e32 v28, s30, v28
	v_mul_f32_e32 v29, s30, v29
	v_mul_f32_e32 v30, s30, v30
	v_mul_f32_e32 v31, s30, v31
	v_exp_f32_e32 v28, v28
	v_exp_f32_e32 v29, v29
	v_exp_f32_e32 v30, v30
	v_exp_f32_e32 v31, v31
	v_add_f32_e32 v28, 1.0, v28
	v_add_f32_e32 v29, 1.0, v29
	v_add_f32_e32 v30, 1.0, v30
	v_add_f32_e32 v31, 1.0, v31
	v_rcp_f32_e32 v28, v28
	v_rcp_f32_e32 v29, v29
	v_rcp_f32_e32 v30, v30
	v_rcp_f32_e32 v31, v31
	v_cvt_pk_bf16_f32 v136, v28, v29
	v_cvt_pk_bf16_f32 v137, v30, v31
	global_store_dwordx2 v64, v[136:137], s[34:35] offset:256
	v_mul_f32_e32 v24, s30, v24
	v_mul_f32_e32 v25, s30, v25
	v_mul_f32_e32 v26, s30, v26
	v_mul_f32_e32 v27, s30, v27
	v_exp_f32_e32 v24, v24
	v_exp_f32_e32 v25, v25
	v_exp_f32_e32 v26, v26
	v_exp_f32_e32 v27, v27
; __device__ __forceinline__ u32x2 pack4(f32x4 v) { u32x2 r; r[0] = cvt_pk(v[0], v[1]); r[1] = cvt_pk(v[2], v[3]); return r; }
; __device__ __forceinline__ float sigmoidf_(float x) { return __builtin_amdgcn_rcpf(1.0f + __expf(-x)); }
; __device__ __forceinline__ float gelu_tanh(float x) { const float z = 1.5957691216057308f * (x + 0.044715f * x * x * x); return x * sigmoidf_(z); }
; __device__ __forceinline__ float siluf_(float x) { return x * sigmoidf_(x); }
; __device__ __forceinline__ void epilogue(const Params& p, const Unit& u, const f32x4 (&acc)[2][2][4][2], int wr, int wc, int fr, int fq) {
;     ...
; #pragma unroll
;     for (int ai = 0; ai < 2; ++ai)
; #pragma unroll
;       for (int m = 0; m < 4; ++m) {
;         bf16_t* rp = dst + (size_t)(row0 + ai * 128 + m * 16) * ld + cb + ct0;
; #pragma unroll
;         for (int bj = 0; bj < 2; ++bj)
; #pragma unroll
;           for (int n = 0; n < 2; ++n) {
;             f32x4 v = acc[ai][bj][m][n];
;             if (act == 1) { v[0] = sigmoidf_(v[0]); v[1] = sigmoidf_(v[1]); v[2] = sigmoidf_(v[2]); v[3] = sigmoidf_(v[3]); }
;             else if (act == 2) { v[0] = gelu_tanh(v[0]); v[1] = gelu_tanh(v[1]); v[2] = gelu_tanh(v[2]); v[3] = gelu_tanh(v[3]); }
;             else if (act == 3) { v[0] = siluf_(v[0]); v[1] = siluf_(v[1]); v[2] = siluf_(v[2]); v[3] = siluf_(v[3]); }
;             else { v = v * scale; }
;             *(u32x2*)(rp + bj * 128 + n * 16) = pack4(v);
;           }
	v_add_f32_e32 v24, 1.0, v24
	v_add_f32_e32 v25, 1.0, v25
	v_add_f32_e32 v26, 1.0, v26
	v_add_f32_e32 v27, 1.0, v27
	v_rcp_f32_e32 v24, v24
	v_rcp_f32_e32 v25, v25
	v_rcp_f32_e32 v26, v26
	v_rcp_f32_e32 v27, v27
	v_cvt_pk_bf16_f32 v138, v24, v25
	v_cvt_pk_bf16_f32 v139, v26, v27
	global_store_dwordx2 v64, v[138:139], s[34:35] offset:288
	v_add_u32_e32 v64, 0x30000, v64
	v_mul_f32_e32 v52, s30, v52
	v_mul_f32_e32 v53, s30, v53
	v_mul_f32_e32 v54, s30, v54
	v_mul_f32_e32 v55, s30, v55
	v_exp_f32_e32 v52, v52
	v_exp_f32_e32 v53, v53
	v_exp_f32_e32 v54, v54
	v_exp_f32_e32 v55, v55
	v_add_f32_e32 v52, 1.0, v52
	v_add_f32_e32 v53, 1.0, v53
	v_add_f32_e32 v54, 1.0, v54
	v_add_f32_e32 v55, 1.0, v55
	v_rcp_f32_e32 v52, v52
	v_rcp_f32_e32 v53, v53
	v_rcp_f32_e32 v54, v54
	v_rcp_f32_e32 v55, v55
	v_cvt_pk_bf16_f32 v140, v52, v53
	v_cvt_pk_bf16_f32 v141, v54, v55
	global_store_dwordx2 v64, v[140:141], s[34:35] offset:0
	v_mul_f32_e32 v48, s30, v48
	v_mul_f32_e32 v49, s30, v49
	v_mul_f32_e32 v50, s30, v50
	v_mul_f32_e32 v51, s30, v51
	v_exp_f32_e32 v48, v48
	v_exp_f32_e32 v49, v49
	v_exp_f32_e32 v50, v50
	v_exp_f32_e32 v51, v51
	v_add_f32_e32 v48, 1.0, v48
	v_add_f32_e32 v49, 1.0, v49
	v_add_f32_e32 v50, 1.0, v50
	v_add_f32_e32 v51, 1.0, v51
	v_rcp_f32_e32 v48, v48
	v_rcp_f32_e32 v49, v49
	v_rcp_f32_e32 v50, v50
	v_rcp_f32_e32 v51, v51
	v_cvt_pk_bf16_f32 v142, v48, v49
	v_cvt_pk_bf16_f32 v143, v50, v51
	global_store_dwordx2 v64, v[142:143], s[34:35] offset:32
	v_mul_f32_e32 v20, s30, v20
	v_mul_f32_e32 v21, s30, v21
	v_mul_f32_e32 v22, s30, v22
	v_mul_f32_e32 v23, s30, v23
	v_exp_f32_e32 v20, v20
	v_exp_f32_e32 v21, v21
	v_exp_f32_e32 v22, v22
	v_exp_f32_e32 v23, v23
	v_add_f32_e32 v20, 1.0, v20
	v_add_f32_e32 v21, 1.0, v21
	v_add_f32_e32 v22, 1.0, v22
	v_add_f32_e32 v23, 1.0, v23
	v_rcp_f32_e32 v20, v20
	v_rcp_f32_e32 v21, v21
	v_rcp_f32_e32 v22, v22
	v_rcp_f32_e32 v23, v23
	v_cvt_pk_bf16_f32 v144, v20, v21
	v_cvt_pk_bf16_f32 v145, v22, v23
	global_store_dwordx2 v64, v[144:145], s[34:35] offset:256
	v_mul_f32_e32 v16, s30, v16
	v_mul_f32_e32 v17, s30, v17
	v_mul_f32_e32 v18, s30, v18
	v_mul_f32_e32 v19, s30, v19
	v_exp_f32_e32 v16, v16
	v_exp_f32_e32 v17, v17
	v_exp_f32_e32 v18, v18
	v_exp_f32_e32 v19, v19
	v_add_f32_e32 v16, 1.0, v16
	v_add_f32_e32 v17, 1.0, v17
	v_add_f32_e32 v18, 1.0, v18
	v_add_f32_e32 v19, 1.0, v19
	v_rcp_f32_e32 v16, v16
	v_rcp_f32_e32 v17, v17
	v_rcp_f32_e32 v18, v18
	v_rcp_f32_e32 v19, v19
	v_cvt_pk_bf16_f32 v146, v16, v17
	v_cvt_pk_bf16_f32 v147, v18, v19
	global_store_dwordx2 v64, v[146:147], s[34:35] offset:288
	v_add_u32_e32 v64, 0x30000, v64
	v_mul_f32_e32 v44, s30, v44
	v_mul_f32_e32 v45, s30, v45
	v_mul_f32_e32 v46, s30, v46
	v_mul_f32_e32 v47, s30, v47
	v_exp_f32_e32 v44, v44
	v_exp_f32_e32 v45, v45
	v_exp_f32_e32 v46, v46
	v_exp_f32_e32 v47, v47
	v_add_f32_e32 v44, 1.0, v44
	v_add_f32_e32 v45, 1.0, v45
	v_add_f32_e32 v46, 1.0, v46
	v_add_f32_e32 v47, 1.0, v47
	v_rcp_f32_e32 v44, v44
	v_rcp_f32_e32 v45, v45
	v_rcp_f32_e32 v46, v46
	v_rcp_f32_e32 v47, v47
	v_cvt_pk_bf16_f32 v132, v44, v45
	v_cvt_pk_bf16_f32 v133, v46, v47
	global_store_dwordx2 v64, v[132:133], s[34:35] offset:0
	v_mul_f32_e32 v40, s30, v40
	v_mul_f32_e32 v41, s30, v41
	v_mul_f32_e32 v42, s30, v42
	v_mul_f32_e32 v43, s30, v43
	v_exp_f32_e32 v40, v40
	v_exp_f32_e32 v41, v41
	v_exp_f32_e32 v42, v42
	v_exp_f32_e32 v43, v43
	v_add_f32_e32 v40, 1.0, v40
	v_add_f32_e32 v41, 1.0, v41
	v_add_f32_e32 v42, 1.0, v42
	v_add_f32_e32 v43, 1.0, v43
	v_rcp_f32_e32 v40, v40
	v_rcp_f32_e32 v41, v41
	v_rcp_f32_e32 v42, v42
	v_rcp_f32_e32 v43, v43
	v_cvt_pk_bf16_f32 v134, v40, v41
	v_cvt_pk_bf16_f32 v135, v42, v43
	global_store_dwordx2 v64, v[134:135], s[34:35] offset:32
	v_mul_f32_e32 v12, s30, v12
	v_mul_f32_e32 v13, s30, v13
	v_mul_f32_e32 v14, s30, v14
	v_mul_f32_e32 v15, s30, v15
	v_exp_f32_e32 v12, v12
	v_exp_f32_e32 v13, v13
	v_exp_f32_e32 v14, v14
	v_exp_f32_e32 v15, v15
	v_add_f32_e32 v12, 1.0, v12
	v_add_f32_e32 v13, 1.0, v13
	v_add_f32_e32 v14, 1.0, v14
	v_add_f32_e32 v15, 1.0, v15
	v_rcp_f32_e32 v12, v12
	v_rcp_f32_e32 v13, v13
	v_rcp_f32_e32 v14, v14
	v_rcp_f32_e32 v15, v15
	v_cvt_pk_bf16_f32 v136, v12, v13
	v_cvt_pk_bf16_f32 v137, v14, v15
	global_store_dwordx2 v64, v[136:137], s[34:35] offset:256
	v_mul_f32_e32 v8, s30, v8
	v_mul_f32_e32 v9, s30, v9
	v_mul_f32_e32 v10, s30, v10
	v_mul_f32_e32 v11, s30, v11
	v_exp_f32_e32 v8, v8
	v_exp_f32_e32 v9, v9
	v_exp_f32_e32 v10, v10
	v_exp_f32_e32 v11, v11
	v_add_f32_e32 v8, 1.0, v8
	v_add_f32_e32 v9, 1.0, v9
	v_add_f32_e32 v10, 1.0, v10
	v_add_f32_e32 v11, 1.0, v11
	v_rcp_f32_e32 v8, v8
	v_rcp_f32_e32 v9, v9
	v_rcp_f32_e32 v10, v10
	v_rcp_f32_e32 v11, v11
	v_cvt_pk_bf16_f32 v138, v8, v9
	v_cvt_pk_bf16_f32 v139, v10, v11
	global_store_dwordx2 v64, v[138:139], s[34:35] offset:288
	v_add_u32_e32 v64, 0x30000, v64
	v_mul_f32_e32 v36, s30, v36
	v_mul_f32_e32 v37, s30, v37
	v_mul_f32_e32 v38, s30, v38
	v_mul_f32_e32 v39, s30, v39
	v_exp_f32_e32 v36, v36
	v_exp_f32_e32 v37, v37
	v_exp_f32_e32 v38, v38
	v_exp_f32_e32 v39, v39
	v_add_f32_e32 v36, 1.0, v36
	v_add_f32_e32 v37, 1.0, v37
	v_add_f32_e32 v38, 1.0, v38
	v_add_f32_e32 v39, 1.0, v39
	v_rcp_f32_e32 v36, v36
	v_rcp_f32_e32 v37, v37
	v_rcp_f32_e32 v38, v38
	v_rcp_f32_e32 v39, v39
	v_cvt_pk_bf16_f32 v140, v36, v37
	v_cvt_pk_bf16_f32 v141, v38, v39
	global_store_dwordx2 v64, v[140:141], s[34:35] offset:0
	v_mul_f32_e32 v32, s30, v32
	v_mul_f32_e32 v33, s30, v33
	v_mul_f32_e32 v34, s30, v34
	v_mul_f32_e32 v35, s30, v35
	v_exp_f32_e32 v32, v32
	v_exp_f32_e32 v33, v33
	v_exp_f32_e32 v34, v34
	v_exp_f32_e32 v35, v35
	v_add_f32_e32 v32, 1.0, v32
	v_add_f32_e32 v33, 1.0, v33
	v_add_f32_e32 v34, 1.0, v34
	v_add_f32_e32 v35, 1.0, v35
	v_rcp_f32_e32 v32, v32
	v_rcp_f32_e32 v33, v33
	v_rcp_f32_e32 v34, v34
	v_rcp_f32_e32 v35, v35
	v_cvt_pk_bf16_f32 v142, v32, v33
	v_cvt_pk_bf16_f32 v143, v34, v35
	global_store_dwordx2 v64, v[142:143], s[34:35] offset:32
	v_mul_f32_e32 v4, s30, v4
	v_mul_f32_e32 v5, s30, v5
	v_mul_f32_e32 v6, s30, v6
	v_mul_f32_e32 v7, s30, v7
	v_exp_f32_e32 v4, v4
	v_exp_f32_e32 v5, v5
	v_exp_f32_e32 v6, v6
	v_exp_f32_e32 v7, v7
	v_add_f32_e32 v4, 1.0, v4
	v_add_f32_e32 v5, 1.0, v5
	v_add_f32_e32 v6, 1.0, v6
	v_add_f32_e32 v7, 1.0, v7
	v_rcp_f32_e32 v4, v4
	v_rcp_f32_e32 v5, v5
	v_rcp_f32_e32 v6, v6
	v_rcp_f32_e32 v7, v7
	v_cvt_pk_bf16_f32 v144, v4, v5
	v_cvt_pk_bf16_f32 v145, v6, v7
	global_store_dwordx2 v64, v[144:145], s[34:35] offset:256
	v_mul_f32_e32 v0, s30, v0
	v_mul_f32_e32 v1, s30, v1
	v_mul_f32_e32 v2, s30, v2
	v_mul_f32_e32 v3, s30, v3
	v_exp_f32_e32 v0, v0
	v_exp_f32_e32 v1, v1
	v_exp_f32_e32 v2, v2
	v_exp_f32_e32 v3, v3
	v_add_f32_e32 v0, 1.0, v0
	v_add_f32_e32 v1, 1.0, v1
	v_add_f32_e32 v2, 1.0, v2
	v_add_f32_e32 v3, 1.0, v3
	v_rcp_f32_e32 v0, v0
	v_rcp_f32_e32 v1, v1
	v_rcp_f32_e32 v2, v2
	v_rcp_f32_e32 v3, v3
	v_cvt_pk_bf16_f32 v146, v0, v1
	v_cvt_pk_bf16_f32 v147, v2, v3
	global_store_dwordx2 v64, v[146:147], s[34:35] offset:288
	s_branch .LBB0_987
